# o34 plus both scan changes: first two S^T reads hoisted per step, and the two scan items of a workgroup staggered by half a step
# speedup vs baseline: 1.0156x; 1.0156x over previous
.Lscan_stag0:
.LBB0_888:
	ds_read_b128 v[246:249], v237
	ds_read_b128 v[250:253], v237 offset:64
	v_lshl_add_u64 v[214:215], s[8:9], 0, v[196:197]
	v_add_co_u32_e32 v98, vcc, s25, v214
	v_lshl_add_u64 v[216:217], s[8:9], 0, v[198:199]
	s_nop 0
	v_addc_co_u32_e32 v99, vcc, 0, v215, vcc
	v_add_co_u32_e32 v102, vcc, s26, v214
	v_lshl_add_u64 v[218:219], s[8:9], 0, v[200:201]
	s_nop 0
	v_addc_co_u32_e32 v103, vcc, 0, v215, vcc
	v_add_co_u32_e32 v106, vcc, s25, v216
	v_lshl_add_u64 v[220:221], s[8:9], 0, v[202:203]
	s_nop 0
	v_addc_co_u32_e32 v107, vcc, 0, v217, vcc
	v_add_co_u32_e32 v110, vcc, s26, v216
	v_lshl_add_u64 v[222:223], s[8:9], 0, v[194:195]
	s_nop 0
	v_addc_co_u32_e32 v111, vcc, 0, v217, vcc
	v_add_co_u32_e32 v114, vcc, s25, v218
	v_lshl_add_u64 v[224:225], s[8:9], 0, v[204:205]
	s_nop 0
	v_addc_co_u32_e32 v115, vcc, 0, v219, vcc
	v_add_co_u32_e32 v118, vcc, s26, v218
	global_load_dwordx4 v[98:101], v[98:99], off
	s_nop 0
	v_addc_co_u32_e32 v119, vcc, 0, v219, vcc
	v_add_co_u32_e32 v122, vcc, s25, v220
	global_load_dwordx4 v[102:105], v[102:103], off
	s_nop 0
	v_addc_co_u32_e32 v123, vcc, 0, v221, vcc
	v_add_co_u32_e32 v126, vcc, s26, v220
	global_load_dwordx4 v[106:109], v[106:107], off
	s_nop 0
	v_addc_co_u32_e32 v127, vcc, 0, v221, vcc
	v_add_co_u32_e32 v130, vcc, s27, v222
	global_load_dwordx4 v[110:113], v[110:111], off
	s_nop 0
	v_addc_co_u32_e32 v131, vcc, 0, v223, vcc
	global_load_dwordx4 v[114:117], v[114:115], off
	v_lshl_add_u64 v[226:227], s[8:9], 0, v[206:207]
	global_load_dwordx4 v[118:121], v[118:119], off
	v_lshl_add_u64 v[228:229], s[8:9], 0, v[208:209]
	global_load_dwordx4 v[122:125], v[122:123], off
	v_lshl_add_u64 v[230:231], s[8:9], 0, v[210:211]
	global_load_dwordx4 v[126:129], v[126:127], off
	s_nop 0
	global_load_dword v241, v[130:131], off
	global_load_dword v242, v[130:131], off offset:256
	global_load_dword v243, v[130:131], off offset:512
	global_load_dword v244, v[130:131], off offset:768
	v_add_co_u32_e32 v130, vcc, s34, v224
	v_lshl_add_u64 v[232:233], s[8:9], 0, v[212:213]
	s_nop 0
	v_addc_co_u32_e32 v131, vcc, 0, v225, vcc
	v_add_co_u32_e32 v134, vcc, s34, v226
	global_load_dwordx4 v[130:133], v[130:131], off
	s_nop 0
	v_addc_co_u32_e32 v135, vcc, 0, v227, vcc
	v_add_co_u32_e32 v146, vcc, s35, v228
	global_load_dwordx4 v[134:137], v[134:135], off
	s_nop 0
	v_addc_co_u32_e32 v147, vcc, 0, v229, vcc
	v_add_co_u32_e32 v142, vcc, s35, v230
	global_load_dwordx4 v[138:141], v[146:147], off
	s_nop 0
	v_addc_co_u32_e32 v143, vcc, 0, v231, vcc
	global_load_dwordx4 v[142:145], v[142:143], off
	s_nop 0
	global_load_dwordx4 v[146:149], v[146:147], off offset:1024

	s_waitcnt vmcnt(37) lgkmcnt(0)
	v_mfma_f32_16x16x32_bf16 v[18:21], v[18:21], v[246:249], 0
	v_add_co_u32_e32 v150, vcc, s35, v232
	s_add_i32 s61, s62, 6
	s_waitcnt vmcnt(31)
	v_mfma_f32_16x16x32_bf16 v[38:41], v[38:41], v[246:249], 0

	v_addc_co_u32_e32 v151, vcc, 0, v233, vcc
	s_waitcnt lgkmcnt(0)
	v_mfma_f32_16x16x32_bf16 v[6:9], v[6:9], v[250:253], v[18:21]
	global_load_dwordx4 v[150:153], v[150:151], off
	s_nop 1
	ds_read_b128 v[18:21], v237 offset:128
	s_add_i32 s65, s62, 7
	v_mfma_f32_16x16x32_bf16 v[2:5], v[2:5], v[250:253], v[38:41]
	v_readlane_b32 s64, v177, s61
	v_readlane_b32 s66, v177, s65
	s_add_i32 s63, s62, 8
	s_waitcnt vmcnt(27) lgkmcnt(0)
	v_mfma_f32_16x16x32_bf16 v[2:5], v[14:17], v[18:21], v[2:5]
	ds_read_b128 v[14:17], v237 offset:192
	v_lshl_add_u64 v[194:195], v[194:195], 0, s[16:17]
	v_lshl_add_u64 v[196:197], v[196:197], 0, s[18:19]
	s_waitcnt vmcnt(21)
	v_mfma_f32_16x16x32_bf16 v[6:9], v[26:29], v[18:21], v[6:9]
	v_mul_f32_e64 v20, v92, s64
	v_mul_f32_e64 v21, v93, s64
	v_pk_mul_f32 v[18:19], v[90:91], s[64:65] op_sel_hi:[1,0]
	v_lshl_add_u64 v[198:199], v[198:199], 0, s[18:19]
	s_waitcnt vmcnt(19) lgkmcnt(0)
	v_mfma_f32_16x16x32_bf16 v[6:9], v[22:25], v[14:17], v[6:9]
	v_lshl_add_u64 v[200:201], v[200:201], 0, s[18:19]
	v_lshl_add_u64 v[202:203], v[202:203], 0, s[18:19]
	v_lshl_add_u64 v[204:205], v[204:205], 0, s[20:21]
	v_mfma_f32_16x16x32_bf16 v[2:5], v[10:13], v[14:17], v[2:5]
	v_mul_f32_e64 v16, v96, s64
	v_mul_f32_e64 v17, v97, s64
	s_nop 1
	v_sub_f32_e32 v9, v240, v9
	v_sub_f32_e32 v8, v239, v8
	v_sub_f32_e32 v7, v238, v7
	v_sub_f32_e32 v6, v193, v6
	v_cvt_pk_bf16_f32 v6, v6, v7
	v_cvt_pk_bf16_f32 v7, v8, v9
	ds_write_b64 v236, v[6:7] offset:4352
	s_waitcnt lgkmcnt(0)
	s_barrier
	ds_read_b128 v[6:9], v235 offset:4352
	ds_read_b128 v[10:13], v235 offset:4416
	v_pk_mul_f32 v[14:15], v[94:95], s[64:65] op_sel_hi:[1,0]
	s_waitcnt lgkmcnt(1)
	v_mfma_f32_16x16x32_bf16 v[2:5], v[86:89], v[6:9], v[2:5]
	v_ashrrev_i32_e32 v193, 31, v192
	s_add_i32 s64, s62, 9
	s_add_i32 s65, s62, 10
	v_mfma_f32_16x16x32_bf16 v[14:17], v[70:73], v[6:9], v[14:17]
	v_readlane_b32 s64, v177, s64
	s_add_i32 s62, s62, 11
	v_readlane_b32 s62, v177, s62
	v_mfma_f32_16x16x32_bf16 v[6:9], v[66:69], v[6:9], v[18:21]
	v_lshl_add_u64 v[206:207], v[206:207], 0, s[20:21]
	v_lshl_add_u64 v[208:209], v[208:209], 0, s[18:19]
	v_lshl_add_u64 v[210:211], v[210:211], 0, s[18:19]
	s_waitcnt lgkmcnt(0)
	v_mfma_f32_16x16x32_bf16 v[90:93], v[82:85], v[10:13], v[14:17]
	v_lshl_add_u64 v[212:213], v[212:213], 0, s[18:19]
	s_cmp_lt_u32 s61, 24
	v_mfma_f32_16x16x32_bf16 v[94:97], v[78:81], v[10:13], v[6:9]
	v_mfma_f32_16x16x32_bf16 v[2:5], v[74:77], v[10:13], v[2:5]
	s_nop 3
	v_cvt_pk_bf16_f32 v6, v90, v91
	v_cvt_pk_bf16_f32 v7, v92, v93
	s_nop 0
	v_cvt_pk_bf16_f32 v8, v94, v95
	v_cvt_pk_bf16_f32 v9, v96, v97
	ds_write2_b64 v234, v[6:7], v[8:9] offset1:4
	v_lshlrev_b64 v[6:7], 12, v[192:193]
	v_lshl_add_u64 v[6:7], v[190:191], 0, v[6:7]
	v_add_co_u32_e32 v8, vcc, s30, v6
	global_store_dword v[6:7], v2, off
	s_nop 0
	v_addc_co_u32_e32 v9, vcc, 0, v7, vcc
	v_add_co_u32_e32 v2, vcc, s31, v6
	global_store_dword v[8:9], v3, off offset:-4096
	global_store_dword v[8:9], v4, off
	v_addc_co_u32_e32 v3, vcc, 0, v7, vcc
	global_store_dword v[2:3], v5, off
	v_add_co_u32_e32 v2, vcc, s36, v214
	s_waitcnt lgkmcnt(0)
	s_barrier
	ds_read_b128 v[246:249], v237
	ds_read_b128 v[250:253], v237 offset:64
	s_nop 0
	v_addc_co_u32_e32 v3, vcc, 0, v215, vcc
	v_add_co_u32_e32 v6, vcc, s37, v214
	global_load_dwordx4 v[2:5], v[2:3], off
	s_nop 0
	v_addc_co_u32_e32 v7, vcc, 0, v215, vcc
	v_add_co_u32_e32 v10, vcc, s36, v216
	global_load_dwordx4 v[6:9], v[6:7], off
	s_nop 0
	v_addc_co_u32_e32 v11, vcc, 0, v217, vcc
	v_add_co_u32_e32 v14, vcc, s37, v216
	global_load_dwordx4 v[10:13], v[10:11], off
	s_nop 0
	v_addc_co_u32_e32 v15, vcc, 0, v217, vcc
	v_add_co_u32_e32 v18, vcc, s36, v218
	global_load_dwordx4 v[14:17], v[14:15], off
	s_nop 0
	v_addc_co_u32_e32 v19, vcc, 0, v219, vcc
	v_add_co_u32_e32 v22, vcc, s37, v218
	global_load_dwordx4 v[18:21], v[18:19], off
	s_nop 0
	v_addc_co_u32_e32 v23, vcc, 0, v219, vcc
	v_add_co_u32_e32 v26, vcc, s36, v220
	global_load_dwordx4 v[22:25], v[22:23], off
	s_nop 0
	v_addc_co_u32_e32 v27, vcc, 0, v221, vcc
	v_add_co_u32_e32 v38, vcc, s37, v220
	global_load_dwordx4 v[26:29], v[26:27], off
	s_nop 0
	v_addc_co_u32_e32 v39, vcc, 0, v221, vcc
	v_add_co_u32_e32 v66, vcc, s38, v222
	global_load_dwordx4 v[38:41], v[38:39], off
	s_nop 0
	v_addc_co_u32_e32 v67, vcc, 0, v223, vcc
	global_load_dword v193, v[66:67], off
	global_load_dword v238, v[66:67], off offset:256
	global_load_dword v239, v[66:67], off offset:512
	global_load_dword v240, v[66:67], off offset:768
	v_add_co_u32_e32 v66, vcc, s39, v224
	s_nop 1
	v_addc_co_u32_e32 v67, vcc, 0, v225, vcc
	v_add_co_u32_e32 v70, vcc, s39, v226
	global_load_dwordx4 v[66:69], v[66:67], off
	s_nop 0
	v_addc_co_u32_e32 v71, vcc, 0, v227, vcc
	v_add_co_u32_e32 v82, vcc, s40, v228
	global_load_dwordx4 v[74:77], v[70:71], off
	s_nop 0
	v_addc_co_u32_e32 v83, vcc, 0, v229, vcc
	v_add_co_u32_e32 v78, vcc, s40, v230
	global_load_dwordx4 v[70:73], v[82:83], off
	s_nop 0
	v_addc_co_u32_e32 v79, vcc, 0, v231, vcc
	global_load_dwordx4 v[78:81], v[78:79], off
	s_nop 0
	global_load_dwordx4 v[82:85], v[82:83], off offset:1024

	s_waitcnt lgkmcnt(0)
	v_mfma_f32_16x16x32_bf16 v[30:33], v[30:33], v[246:249], 0
	v_add_co_u32_e32 v86, vcc, s40, v232
	v_mfma_f32_16x16x32_bf16 v[34:37], v[34:37], v[246:249], 0

	s_nop 0
	v_addc_co_u32_e32 v87, vcc, 0, v233, vcc
	s_waitcnt lgkmcnt(0)
	v_mfma_f32_16x16x32_bf16 v[30:33], v[46:49], v[250:253], v[30:33]
	ds_read_b128 v[46:49], v237 offset:128
	global_load_dwordx4 v[86:89], v[86:87], off
	s_waitcnt lgkmcnt(0)
	v_mfma_f32_16x16x32_bf16 v[30:33], v[42:45], v[46:49], v[30:33]
	ds_read_b128 v[42:45], v237 offset:192
	v_mfma_f32_16x16x32_bf16 v[34:37], v[50:53], v[250:253], v[34:37]
	v_mul_f32_e64 v52, v96, s66
	v_mul_f32_e64 v53, v97, s66
	v_pk_mul_f32 v[50:51], v[94:95], s[66:67] op_sel_hi:[1,0]
	s_waitcnt lgkmcnt(0)
	v_mfma_f32_16x16x32_bf16 v[30:33], v[58:61], v[42:45], v[30:33]
	v_mfma_f32_16x16x32_bf16 v[34:37], v[54:57], v[46:49], v[34:37]
	v_mul_f32_e64 v48, v92, s66
	v_mul_f32_e64 v49, v93, s66
	s_nop 4
	v_sub_f32_e32 v33, v156, v33
	v_sub_f32_e32 v32, v155, v32
	v_sub_f32_e32 v31, v154, v31
	s_waitcnt vmcnt(40)
	v_sub_f32_e32 v30, v157, v30
	v_cvt_pk_bf16_f32 v30, v30, v31
	v_cvt_pk_bf16_f32 v31, v32, v33
	ds_write_b64 v236, v[30:31] offset:4352
	s_waitcnt lgkmcnt(0)
	s_barrier
	v_mfma_f32_16x16x32_bf16 v[34:37], v[62:65], v[42:45], v[34:37]
	ds_read_b128 v[30:33], v235 offset:4352
	ds_read_b128 v[42:45], v235 offset:4416
	v_pk_mul_f32 v[46:47], v[90:91], s[66:67] op_sel_hi:[1,0]
	v_readlane_b32 s66, v177, s63
	s_waitcnt vmcnt(27) lgkmcnt(1)
	v_mfma_f32_16x16x32_bf16 v[34:37], v[130:133], v[30:33], v[34:37]
	s_waitcnt vmcnt(25)
	v_mfma_f32_16x16x32_bf16 v[46:49], v[138:141], v[30:33], v[46:49]
	s_waitcnt vmcnt(23)
	v_mfma_f32_16x16x32_bf16 v[30:33], v[146:149], v[30:33], v[50:53]
	s_waitcnt lgkmcnt(0)
	v_mfma_f32_16x16x32_bf16 v[90:93], v[142:145], v[42:45], v[46:49]
	s_waitcnt vmcnt(22)
	v_mfma_f32_16x16x32_bf16 v[94:97], v[150:153], v[42:45], v[30:33]
	v_mfma_f32_16x16x32_bf16 v[34:37], v[134:137], v[42:45], v[34:37]
	s_nop 4
	v_cvt_pk_bf16_f32 v30, v90, v91
	v_cvt_pk_bf16_f32 v31, v92, v93
	v_cvt_pk_bf16_f32 v32, v94, v95
	v_cvt_pk_bf16_f32 v33, v96, v97
	ds_write2_b64 v234, v[30:31], v[32:33] offset1:4
	v_add_u32_e32 v30, 64, v192
	v_ashrrev_i32_e32 v31, 31, v30
	v_lshlrev_b64 v[30:31], 12, v[30:31]
	v_lshl_add_u64 v[30:31], v[190:191], 0, v[30:31]
	v_add_co_u32_e32 v32, vcc, s30, v30
	global_store_dword v[30:31], v34, off
	s_nop 0
	v_addc_co_u32_e32 v33, vcc, 0, v31, vcc
	v_add_co_u32_e32 v30, vcc, s31, v30
	global_store_dword v[32:33], v35, off offset:-4096
	global_store_dword v[32:33], v36, off
	v_addc_co_u32_e32 v31, vcc, 0, v31, vcc
	global_store_dword v[30:31], v37, off
	v_add_co_u32_e32 v30, vcc, s41, v214
	s_waitcnt lgkmcnt(0)
	s_barrier
	ds_read_b128 v[154:157], v237
	ds_read_b128 v[250:253], v237 offset:64
	s_nop 0
	v_addc_co_u32_e32 v31, vcc, 0, v215, vcc
	v_add_co_u32_e32 v34, vcc, s42, v214
	global_load_dwordx4 v[30:33], v[30:31], off
	s_nop 0
	v_addc_co_u32_e32 v35, vcc, 0, v215, vcc
	v_add_co_u32_e32 v42, vcc, s41, v216
	global_load_dwordx4 v[34:37], v[34:35], off
	s_nop 0
	v_addc_co_u32_e32 v43, vcc, 0, v217, vcc
	v_add_co_u32_e32 v46, vcc, s42, v216
	global_load_dwordx4 v[42:45], v[42:43], off
	s_nop 0
	v_addc_co_u32_e32 v47, vcc, 0, v217, vcc
	v_add_co_u32_e32 v50, vcc, s41, v218
	global_load_dwordx4 v[46:49], v[46:47], off
	s_nop 0
	v_addc_co_u32_e32 v51, vcc, 0, v219, vcc
	v_add_co_u32_e32 v54, vcc, s42, v218
	global_load_dwordx4 v[50:53], v[50:51], off
	s_nop 0
	v_addc_co_u32_e32 v55, vcc, 0, v219, vcc
	v_add_co_u32_e32 v58, vcc, s41, v220
	global_load_dwordx4 v[54:57], v[54:55], off
	s_nop 0
	v_addc_co_u32_e32 v59, vcc, 0, v221, vcc
	v_add_co_u32_e32 v62, vcc, s42, v220
	global_load_dwordx4 v[58:61], v[58:59], off
	s_nop 0
	v_addc_co_u32_e32 v63, vcc, 0, v221, vcc
	v_add_co_u32_e32 v130, vcc, s43, v222
	global_load_dwordx4 v[62:65], v[62:63], off
	s_nop 0
	v_addc_co_u32_e32 v131, vcc, 0, v223, vcc
	global_load_dword v245, v[130:131], off
	global_load_dword v246, v[130:131], off offset:256
	global_load_dword v247, v[130:131], off offset:512
	global_load_dword v248, v[130:131], off offset:768
	v_add_co_u32_e32 v130, vcc, s44, v224
	s_nop 1
	v_addc_co_u32_e32 v131, vcc, 0, v225, vcc
	v_add_co_u32_e32 v134, vcc, s44, v226
	global_load_dwordx4 v[130:133], v[130:131], off
	s_nop 0
	v_addc_co_u32_e32 v135, vcc, 0, v227, vcc
	v_add_co_u32_e32 v146, vcc, s45, v228
	global_load_dwordx4 v[138:141], v[134:135], off
	s_nop 0
	v_addc_co_u32_e32 v147, vcc, 0, v229, vcc
	v_add_co_u32_e32 v142, vcc, s45, v230
	global_load_dwordx4 v[134:137], v[146:147], off
	s_nop 0
	v_addc_co_u32_e32 v143, vcc, 0, v231, vcc
	global_load_dwordx4 v[142:145], v[142:143], off
	s_nop 0
	global_load_dwordx4 v[146:149], v[146:147], off offset:1024

	s_waitcnt lgkmcnt(0)
	v_mfma_f32_16x16x32_bf16 v[98:101], v[98:101], v[154:157], 0
	v_add_co_u32_e32 v150, vcc, s45, v232
	v_mfma_f32_16x16x32_bf16 v[102:105], v[102:105], v[154:157], 0

	s_nop 0
	v_addc_co_u32_e32 v151, vcc, 0, v233, vcc
	s_waitcnt lgkmcnt(0)
	v_mfma_f32_16x16x32_bf16 v[98:101], v[106:109], v[250:253], v[98:101]
	ds_read_b128 v[106:109], v237 offset:128
	global_load_dwordx4 v[150:153], v[150:151], off
	v_mfma_f32_16x16x32_bf16 v[102:105], v[110:113], v[250:253], v[102:105]
	s_waitcnt lgkmcnt(0)
	v_mfma_f32_16x16x32_bf16 v[98:101], v[114:117], v[106:109], v[98:101]
	v_mfma_f32_16x16x32_bf16 v[102:105], v[118:121], v[106:109], v[102:105]
	ds_read_b128 v[106:109], v237 offset:192
	s_waitcnt lgkmcnt(0)
	v_mfma_f32_16x16x32_bf16 v[98:101], v[122:125], v[106:109], v[98:101]
	v_mfma_f32_16x16x32_bf16 v[102:105], v[126:129], v[106:109], v[102:105]
	s_nop 6
	v_sub_f32_e32 v101, v244, v101
	v_sub_f32_e32 v100, v243, v100
	v_sub_f32_e32 v99, v242, v99
	v_sub_f32_e32 v98, v241, v98
	v_cvt_pk_bf16_f32 v98, v98, v99
	v_cvt_pk_bf16_f32 v99, v100, v101
	ds_write_b64 v236, v[98:99] offset:4352
	s_waitcnt lgkmcnt(0)
	s_barrier
	ds_read_b128 v[98:101], v235 offset:4352
	ds_read_b128 v[106:109], v235 offset:4416
	s_waitcnt vmcnt(27) lgkmcnt(1)
	v_mfma_f32_16x16x32_bf16 v[66:69], v[66:69], v[98:101], v[102:105]
	s_waitcnt vmcnt(26) lgkmcnt(0)
	v_mfma_f32_16x16x32_bf16 v[66:69], v[74:77], v[106:109], v[66:69]
	v_mul_f32_e64 v76, v92, s66
	v_mul_f32_e64 v77, v93, s66
	v_pk_mul_f32 v[74:75], v[90:91], s[66:67] op_sel_hi:[1,0]
	v_pk_mul_f32 v[92:93], v[96:97], s[66:67] op_sel_hi:[1,0]
	v_pk_mul_f32 v[90:91], v[94:95], s[66:67] op_sel_hi:[1,0]
	s_waitcnt vmcnt(25)
	v_mfma_f32_16x16x32_bf16 v[70:73], v[70:73], v[98:101], v[74:77]
	s_waitcnt vmcnt(24)
	v_mfma_f32_16x16x32_bf16 v[122:125], v[78:81], v[106:109], v[70:73]
	s_waitcnt vmcnt(23)
	v_mfma_f32_16x16x32_bf16 v[70:73], v[82:85], v[98:101], v[90:93]
	s_waitcnt vmcnt(22)
	v_mfma_f32_16x16x32_bf16 v[126:129], v[86:89], v[106:109], v[70:73]
	s_nop 5
	v_cvt_pk_bf16_f32 v70, v122, v123
	v_cvt_pk_bf16_f32 v71, v124, v125
	v_cvt_pk_bf16_f32 v72, v126, v127
	v_cvt_pk_bf16_f32 v73, v128, v129
	ds_write2_b64 v234, v[70:71], v[72:73] offset1:4
	v_add_u32_e32 v70, 0x80, v192
	v_ashrrev_i32_e32 v71, 31, v70
	v_lshlrev_b64 v[70:71], 12, v[70:71]
	v_lshl_add_u64 v[70:71], v[190:191], 0, v[70:71]
	v_add_co_u32_e32 v72, vcc, s30, v70
	global_store_dword v[70:71], v66, off
	s_nop 0
	v_addc_co_u32_e32 v73, vcc, 0, v71, vcc
	v_add_co_u32_e32 v66, vcc, s31, v70
	global_store_dword v[72:73], v67, off offset:-4096
	global_store_dword v[72:73], v68, off
	v_addc_co_u32_e32 v67, vcc, 0, v71, vcc
	global_store_dword v[66:67], v69, off
	v_add_co_u32_e32 v66, vcc, s46, v214
	s_waitcnt lgkmcnt(0)
	s_barrier
	ds_read_b128 v[154:157], v237
	ds_read_b128 v[250:253], v237 offset:64
	s_nop 0
	v_addc_co_u32_e32 v67, vcc, 0, v215, vcc
	global_load_dwordx4 v[90:93], v[66:67], off
	v_add_co_u32_e32 v66, vcc, s47, v214
	s_nop 1
	v_addc_co_u32_e32 v67, vcc, 0, v215, vcc
	global_load_dwordx4 v[94:97], v[66:67], off
	v_add_co_u32_e32 v66, vcc, s46, v216
	s_nop 1
	v_addc_co_u32_e32 v67, vcc, 0, v217, vcc
	global_load_dwordx4 v[98:101], v[66:67], off
	v_add_co_u32_e32 v66, vcc, s47, v216
	s_nop 1
	v_addc_co_u32_e32 v67, vcc, 0, v217, vcc
	global_load_dwordx4 v[102:105], v[66:67], off
	v_add_co_u32_e32 v66, vcc, s46, v218
	s_nop 1
	v_addc_co_u32_e32 v67, vcc, 0, v219, vcc
	global_load_dwordx4 v[106:109], v[66:67], off
	v_add_co_u32_e32 v66, vcc, s47, v218
	s_nop 1
	v_addc_co_u32_e32 v67, vcc, 0, v219, vcc
	global_load_dwordx4 v[110:113], v[66:67], off
	v_add_co_u32_e32 v66, vcc, s46, v220
	s_nop 1
	v_addc_co_u32_e32 v67, vcc, 0, v221, vcc
	global_load_dwordx4 v[114:117], v[66:67], off
	v_add_co_u32_e32 v66, vcc, s47, v220
	s_nop 1
	v_addc_co_u32_e32 v67, vcc, 0, v221, vcc
	global_load_dwordx4 v[118:121], v[66:67], off
	v_add_co_u32_e32 v66, vcc, s48, v222
	s_nop 1
	v_addc_co_u32_e32 v67, vcc, 0, v223, vcc
	global_load_dword v241, v[66:67], off
	global_load_dword v242, v[66:67], off offset:256
	global_load_dword v243, v[66:67], off offset:512
	global_load_dword v244, v[66:67], off offset:768
	v_add_co_u32_e32 v66, vcc, s49, v224
	s_nop 1
	v_addc_co_u32_e32 v67, vcc, 0, v225, vcc
	v_add_co_u32_e32 v70, vcc, s49, v226
	global_load_dwordx4 v[66:69], v[66:67], off
	s_nop 0
	v_addc_co_u32_e32 v71, vcc, 0, v227, vcc
	v_add_co_u32_e32 v82, vcc, s50, v228
	global_load_dwordx4 v[74:77], v[70:71], off
	s_nop 0
	v_addc_co_u32_e32 v83, vcc, 0, v229, vcc
	v_add_co_u32_e32 v78, vcc, s50, v230
	global_load_dwordx4 v[70:73], v[82:83], off
	s_nop 0
	v_addc_co_u32_e32 v79, vcc, 0, v231, vcc
	global_load_dwordx4 v[78:81], v[78:79], off
	s_nop 0
	global_load_dwordx4 v[82:85], v[82:83], off offset:1024

	s_waitcnt lgkmcnt(0)
	v_mfma_f32_16x16x32_bf16 v[2:5], v[2:5], v[154:157], 0
	v_add_co_u32_e32 v86, vcc, s50, v232
	v_mfma_f32_16x16x32_bf16 v[6:9], v[6:9], v[154:157], 0

	s_nop 0
	v_addc_co_u32_e32 v87, vcc, 0, v233, vcc
	s_waitcnt lgkmcnt(0)
	v_mfma_f32_16x16x32_bf16 v[2:5], v[10:13], v[250:253], v[2:5]
	ds_read_b128 v[10:13], v237 offset:128
	global_load_dwordx4 v[86:89], v[86:87], off
	v_mfma_f32_16x16x32_bf16 v[6:9], v[14:17], v[250:253], v[6:9]
	s_waitcnt lgkmcnt(0)
	v_mfma_f32_16x16x32_bf16 v[2:5], v[18:21], v[10:13], v[2:5]
	v_mul_f32_e64 v20, v128, s64
	v_mul_f32_e64 v21, v129, s64
	v_pk_mul_f32 v[18:19], v[126:127], s[64:65] op_sel_hi:[1,0]
	v_mfma_f32_16x16x32_bf16 v[6:9], v[22:25], v[10:13], v[6:9]
	ds_read_b128 v[10:13], v237 offset:192
	s_waitcnt lgkmcnt(0)
	v_mfma_f32_16x16x32_bf16 v[2:5], v[26:29], v[10:13], v[2:5]
	v_mfma_f32_16x16x32_bf16 v[6:9], v[38:41], v[10:13], v[6:9]
	s_nop 6
	v_sub_f32_e32 v5, v240, v5
	v_sub_f32_e32 v4, v239, v4
	v_sub_f32_e32 v3, v238, v3
	v_sub_f32_e32 v2, v193, v2
	v_cvt_pk_bf16_f32 v2, v2, v3
	v_cvt_pk_bf16_f32 v3, v4, v5
	ds_write_b64 v236, v[2:3] offset:4352
	s_waitcnt lgkmcnt(0)
	s_barrier
	ds_read_b128 v[10:13], v235 offset:4352
	ds_read_b128 v[14:17], v235 offset:4416
	s_waitcnt vmcnt(27) lgkmcnt(1)
	v_mfma_f32_16x16x32_bf16 v[2:5], v[130:133], v[10:13], v[6:9]
	s_nop 2
	v_mul_f32_e64 v8, v124, s64
	v_mul_f32_e64 v9, v125, s64
	v_pk_mul_f32 v[6:7], v[122:123], s[64:65] op_sel_hi:[1,0]
	v_readlane_b32 s64, v177, s65
	s_waitcnt vmcnt(26) lgkmcnt(0)
	v_mfma_f32_16x16x32_bf16 v[2:5], v[138:141], v[14:17], v[2:5]
	s_waitcnt vmcnt(25)
	v_mfma_f32_16x16x32_bf16 v[6:9], v[134:137], v[10:13], v[6:9]
	s_waitcnt vmcnt(24)
	v_mfma_f32_16x16x32_bf16 v[154:157], v[142:145], v[14:17], v[6:9]
	s_waitcnt vmcnt(23)
	v_mfma_f32_16x16x32_bf16 v[6:9], v[146:149], v[10:13], v[18:21]
	s_waitcnt vmcnt(22)
	v_mfma_f32_16x16x32_bf16 v[146:149], v[150:153], v[14:17], v[6:9]
	s_nop 5
	v_cvt_pk_bf16_f32 v6, v154, v155
	v_cvt_pk_bf16_f32 v7, v156, v157
	v_cvt_pk_bf16_f32 v8, v146, v147
	v_cvt_pk_bf16_f32 v9, v148, v149
	ds_write2_b64 v234, v[6:7], v[8:9] offset1:4
	v_add_u32_e32 v6, 0xc0, v192
	v_ashrrev_i32_e32 v7, 31, v6
	v_lshlrev_b64 v[6:7], 12, v[6:7]
	v_lshl_add_u64 v[6:7], v[190:191], 0, v[6:7]
	v_add_co_u32_e32 v8, vcc, s30, v6
	global_store_dword v[6:7], v2, off
	s_nop 0
	v_addc_co_u32_e32 v9, vcc, 0, v7, vcc
	v_add_co_u32_e32 v2, vcc, s31, v6
	global_store_dword v[8:9], v3, off offset:-4096
	global_store_dword v[8:9], v4, off
	v_addc_co_u32_e32 v3, vcc, 0, v7, vcc
	global_store_dword v[2:3], v5, off
	v_add_co_u32_e32 v2, vcc, s51, v214
	s_waitcnt lgkmcnt(0)
	s_barrier
	ds_read_b128 v[150:153], v237
	ds_read_b128 v[250:253], v237 offset:64
	s_nop 0
	v_addc_co_u32_e32 v3, vcc, 0, v215, vcc
	global_load_dwordx4 v[18:21], v[2:3], off
	v_add_co_u32_e32 v2, vcc, s52, v214
	s_nop 1
	v_addc_co_u32_e32 v3, vcc, 0, v215, vcc
	global_load_dwordx4 v[38:41], v[2:3], off
	v_add_co_u32_e32 v2, vcc, s51, v216
	s_nop 1
	v_addc_co_u32_e32 v3, vcc, 0, v217, vcc
	global_load_dwordx4 v[6:9], v[2:3], off
	v_add_co_u32_e32 v2, vcc, s52, v216
	s_nop 1
	v_addc_co_u32_e32 v3, vcc, 0, v217, vcc
	v_add_co_u32_e32 v10, vcc, s51, v218
	global_load_dwordx4 v[2:5], v[2:3], off
	s_nop 0
	v_addc_co_u32_e32 v11, vcc, 0, v219, vcc
	global_load_dwordx4 v[26:29], v[10:11], off
	v_add_co_u32_e32 v10, vcc, s52, v218
	s_nop 1
	v_addc_co_u32_e32 v11, vcc, 0, v219, vcc
	global_load_dwordx4 v[14:17], v[10:11], off
	v_add_co_u32_e32 v10, vcc, s51, v220
	s_nop 1
	v_addc_co_u32_e32 v11, vcc, 0, v221, vcc
	global_load_dwordx4 v[22:25], v[10:11], off
	v_add_co_u32_e32 v10, vcc, s52, v220
	s_nop 1
	v_addc_co_u32_e32 v11, vcc, 0, v221, vcc
	v_add_co_u32_e32 v122, vcc, s53, v222
	global_load_dwordx4 v[10:13], v[10:11], off
	s_nop 0
	v_addc_co_u32_e32 v123, vcc, 0, v223, vcc
	global_load_dword v193, v[122:123], off
	global_load_dword v238, v[122:123], off offset:256
	global_load_dword v239, v[122:123], off offset:512
	global_load_dword v240, v[122:123], off offset:768
	v_add_co_u32_e32 v122, vcc, s54, v224
	s_nop 1
	v_addc_co_u32_e32 v123, vcc, 0, v225, vcc
	v_add_co_u32_e32 v126, vcc, s54, v226
	global_load_dwordx4 v[122:125], v[122:123], off
	s_nop 0
	v_addc_co_u32_e32 v127, vcc, 0, v227, vcc
	v_add_co_u32_e32 v138, vcc, s55, v228
	global_load_dwordx4 v[130:133], v[126:127], off
	s_nop 0
	v_addc_co_u32_e32 v139, vcc, 0, v229, vcc
	v_add_co_u32_e32 v134, vcc, s55, v230
	global_load_dwordx4 v[126:129], v[138:139], off
	s_nop 0
	v_addc_co_u32_e32 v135, vcc, 0, v231, vcc
	global_load_dwordx4 v[134:137], v[134:135], off
	s_nop 0
	global_load_dwordx4 v[138:141], v[138:139], off offset:1024

	s_waitcnt lgkmcnt(0)
	v_mfma_f32_16x16x32_bf16 v[30:33], v[30:33], v[150:153], 0
	v_add_co_u32_e32 v142, vcc, s55, v232
	v_mfma_f32_16x16x32_bf16 v[34:37], v[34:37], v[150:153], 0

	s_nop 0
	v_addc_co_u32_e32 v143, vcc, 0, v233, vcc
	s_waitcnt lgkmcnt(0)
	v_mfma_f32_16x16x32_bf16 v[30:33], v[42:45], v[250:253], v[30:33]
	ds_read_b128 v[42:45], v237 offset:128
	global_load_dwordx4 v[142:145], v[142:143], off
	v_mfma_f32_16x16x32_bf16 v[34:37], v[46:49], v[250:253], v[34:37]
	s_waitcnt lgkmcnt(0)
	v_mfma_f32_16x16x32_bf16 v[30:33], v[50:53], v[42:45], v[30:33]
	v_mul_f32_e64 v52, v148, s64
	v_mul_f32_e64 v53, v149, s64
	v_pk_mul_f32 v[50:51], v[146:147], s[64:65] op_sel_hi:[1,0]
	v_mfma_f32_16x16x32_bf16 v[34:37], v[54:57], v[42:45], v[34:37]
	ds_read_b128 v[42:45], v237 offset:192
	s_waitcnt lgkmcnt(0)
	v_mfma_f32_16x16x32_bf16 v[30:33], v[58:61], v[42:45], v[30:33]
	v_mfma_f32_16x16x32_bf16 v[34:37], v[62:65], v[42:45], v[34:37]
	s_nop 6
	v_sub_f32_e32 v33, v248, v33
	v_sub_f32_e32 v32, v247, v32
	v_sub_f32_e32 v31, v246, v31
	v_sub_f32_e32 v30, v245, v30
	v_cvt_pk_bf16_f32 v30, v30, v31
	v_cvt_pk_bf16_f32 v31, v32, v33
	ds_write_b64 v236, v[30:31] offset:4352
	s_waitcnt lgkmcnt(0)
	s_barrier
	ds_read_b128 v[42:45], v235 offset:4352
	ds_read_b128 v[46:49], v235 offset:4416
	s_waitcnt vmcnt(27) lgkmcnt(1)
	v_mfma_f32_16x16x32_bf16 v[30:33], v[66:69], v[42:45], v[34:37]
	s_nop 2
	v_mul_f32_e64 v36, v156, s64
	v_mul_f32_e64 v37, v157, s64
	v_pk_mul_f32 v[34:35], v[154:155], s[64:65] op_sel_hi:[1,0]
	s_waitcnt vmcnt(26) lgkmcnt(0)
	v_mfma_f32_16x16x32_bf16 v[30:33], v[74:77], v[46:49], v[30:33]
	s_waitcnt vmcnt(25)
	v_mfma_f32_16x16x32_bf16 v[34:37], v[70:73], v[42:45], v[34:37]
	s_waitcnt vmcnt(24)
	v_mfma_f32_16x16x32_bf16 v[146:149], v[78:81], v[46:49], v[34:37]
	s_waitcnt vmcnt(23)
	v_mfma_f32_16x16x32_bf16 v[34:37], v[82:85], v[42:45], v[50:53]
	s_waitcnt vmcnt(22)
	v_mfma_f32_16x16x32_bf16 v[150:153], v[86:89], v[46:49], v[34:37]
	s_nop 5
	v_cvt_pk_bf16_f32 v34, v146, v147
	v_cvt_pk_bf16_f32 v35, v148, v149
	v_cvt_pk_bf16_f32 v36, v150, v151
	v_cvt_pk_bf16_f32 v37, v152, v153
	ds_write2_b64 v234, v[34:35], v[36:37] offset1:4
	v_add_u32_e32 v34, 0x100, v192
	v_ashrrev_i32_e32 v35, 31, v34
	v_lshlrev_b64 v[34:35], 12, v[34:35]
	v_lshl_add_u64 v[34:35], v[190:191], 0, v[34:35]
	v_add_co_u32_e32 v36, vcc, s30, v34
	global_store_dword v[34:35], v30, off
	s_nop 0
	v_addc_co_u32_e32 v37, vcc, 0, v35, vcc
	v_add_co_u32_e32 v30, vcc, s31, v34
	global_store_dword v[36:37], v31, off offset:-4096
	global_store_dword v[36:37], v32, off
	v_addc_co_u32_e32 v31, vcc, 0, v35, vcc
	global_store_dword v[30:31], v33, off
	v_add_co_u32_e32 v30, vcc, s56, v214
	s_waitcnt lgkmcnt(0)
	s_barrier
	s_nop 0
	v_addc_co_u32_e32 v31, vcc, 0, v215, vcc
	v_add_co_u32_e32 v34, vcc, s57, v214
	global_load_dwordx4 v[30:33], v[30:31], off
	s_nop 0
	v_addc_co_u32_e32 v35, vcc, 0, v215, vcc
	v_add_co_u32_e32 v42, vcc, s56, v216
	global_load_dwordx4 v[34:37], v[34:35], off
	s_nop 0
	v_addc_co_u32_e32 v43, vcc, 0, v217, vcc
	global_load_dwordx4 v[46:49], v[42:43], off
	v_add_co_u32_e32 v42, vcc, s57, v216
	s_nop 1
	v_addc_co_u32_e32 v43, vcc, 0, v217, vcc
	ds_read_b128 v[214:217], v237
	ds_read_b128 v[250:253], v237 offset:64
	global_load_dwordx4 v[50:53], v[42:43], off
	v_add_co_u32_e32 v42, vcc, s56, v218
	s_nop 1
	v_addc_co_u32_e32 v43, vcc, 0, v219, vcc
	v_add_co_u32_e32 v54, vcc, s57, v218
	global_load_dwordx4 v[42:45], v[42:43], off
	s_nop 0
	v_addc_co_u32_e32 v55, vcc, 0, v219, vcc
	v_add_co_u32_e32 v58, vcc, s56, v220
	global_load_dwordx4 v[54:57], v[54:55], off
	s_nop 0
	v_addc_co_u32_e32 v59, vcc, 0, v221, vcc
	v_add_co_u32_e32 v62, vcc, s57, v220
	global_load_dwordx4 v[58:61], v[58:59], off
	s_nop 0
	v_addc_co_u32_e32 v63, vcc, 0, v221, vcc
	v_add_co_u32_e32 v66, vcc, s58, v222
	global_load_dwordx4 v[62:65], v[62:63], off
	s_nop 0
	v_addc_co_u32_e32 v67, vcc, 0, v223, vcc
	global_load_dword v157, v[66:67], off
	global_load_dword v154, v[66:67], off offset:256
	global_load_dword v155, v[66:67], off offset:512
	global_load_dword v156, v[66:67], off offset:768
	v_add_co_u32_e32 v66, vcc, s59, v224
	s_nop 1
	v_addc_co_u32_e32 v67, vcc, 0, v225, vcc
	global_load_dwordx4 v[86:89], v[66:67], off
	v_add_co_u32_e32 v66, vcc, s59, v226
	s_nop 1
	v_addc_co_u32_e32 v67, vcc, 0, v227, vcc
	global_load_dwordx4 v[74:77], v[66:67], off
	v_add_co_u32_e32 v66, vcc, s60, v228
	s_nop 1
	v_addc_co_u32_e32 v67, vcc, 0, v229, vcc
	v_add_co_u32_e32 v68, vcc, s60, v230
	global_load_dwordx4 v[70:73], v[66:67], off
	s_nop 0
	v_addc_co_u32_e32 v69, vcc, 0, v231, vcc
	v_add_co_u32_e32 v78, vcc, s60, v232
	global_load_dwordx4 v[82:85], v[68:69], off
	s_nop 0
	global_load_dwordx4 v[66:69], v[66:67], off offset:1024
	v_addc_co_u32_e32 v79, vcc, 0, v233, vcc
	global_load_dwordx4 v[78:81], v[78:79], off

	s_waitcnt lgkmcnt(0)
	v_mfma_f32_16x16x32_bf16 v[90:93], v[90:93], v[214:217], 0
	v_mfma_f32_16x16x32_bf16 v[94:97], v[94:97], v[214:217], 0

; DEV void gdn_scan_item(const Params& p, int item, unsigned char* lds) {
;     ...
;     LOAD_E(E0, 0); LOAD_L(L0, 0); LOAD_E(E1, 1);
;     __syncthreads();
;     for (int ch = 0; ch < 30; ch += 6) {
;         SCAN_STEP(E0, E2, L0, L1, ch);     SCAN_STEP(E1, E0, L1, L0, ch + 1); SCAN_STEP(E2, E1, L0, L1, ch + 2);
;         SCAN_STEP(E0, E2, L1, L0, ch + 3); SCAN_STEP(E1, E0, L0, L1, ch + 4); SCAN_STEP(E2, E1, L1, L0, ch + 5);
;     }
;     SCAN_STEP(E0, E2, L0, L1, 30); SCAN_STEP(E1, E0, L1, L0, 31);
	s_waitcnt lgkmcnt(0)
	v_mfma_f32_16x16x32_bf16 v[90:93], v[98:101], v[250:253], v[90:93]
	ds_read_b128 v[98:101], v237 offset:128
	v_mfma_f32_16x16x32_bf16 v[94:97], v[102:105], v[250:253], v[94:97]
	s_waitcnt lgkmcnt(0)
	v_mfma_f32_16x16x32_bf16 v[90:93], v[106:109], v[98:101], v[90:93]
	v_mul_f32_e64 v108, v152, s62
	v_mul_f32_e64 v109, v153, s62
	v_pk_mul_f32 v[106:107], v[150:151], s[62:63] op_sel_hi:[1,0]
	v_mfma_f32_16x16x32_bf16 v[94:97], v[110:113], v[98:101], v[94:97]
	ds_read_b128 v[98:101], v237 offset:192
	s_waitcnt lgkmcnt(0)
	v_mfma_f32_16x16x32_bf16 v[90:93], v[114:117], v[98:101], v[90:93]
	v_mfma_f32_16x16x32_bf16 v[94:97], v[118:121], v[98:101], v[94:97]
	s_nop 6
	v_sub_f32_e32 v93, v244, v93
	v_sub_f32_e32 v92, v243, v92
	v_sub_f32_e32 v91, v242, v91
	v_sub_f32_e32 v90, v241, v90
	v_cvt_pk_bf16_f32 v90, v90, v91
	v_cvt_pk_bf16_f32 v91, v92, v93
	ds_write_b64 v236, v[90:91] offset:4352
	s_waitcnt lgkmcnt(0)
	s_barrier
	ds_read_b128 v[90:93], v235 offset:4352
	ds_read_b128 v[102:105], v235 offset:4416
	s_waitcnt vmcnt(27) lgkmcnt(1)
	v_mfma_f32_16x16x32_bf16 v[94:97], v[122:125], v[90:93], v[94:97]
	s_waitcnt vmcnt(26) lgkmcnt(0)
	v_mfma_f32_16x16x32_bf16 v[98:101], v[130:133], v[102:105], v[94:97]
	s_nop 5
	v_mul_f32_e64 v96, v148, s62
	v_mul_f32_e64 v97, v149, s62
	v_pk_mul_f32 v[94:95], v[146:147], s[62:63] op_sel_hi:[1,0]
	s_mov_b32 s62, s61
	s_waitcnt vmcnt(25)
	v_mfma_f32_16x16x32_bf16 v[94:97], v[126:129], v[90:93], v[94:97]
	s_waitcnt vmcnt(23)
	v_mfma_f32_16x16x32_bf16 v[90:93], v[138:141], v[90:93], v[106:109]
	v_mfma_f32_16x16x32_bf16 v[94:97], v[134:137], v[102:105], v[94:97]
	s_waitcnt vmcnt(22)
	v_mfma_f32_16x16x32_bf16 v[90:93], v[142:145], v[102:105], v[90:93]
	s_nop 5
	v_cvt_pk_bf16_f32 v102, v94, v95
	v_cvt_pk_bf16_f32 v103, v96, v97
	v_cvt_pk_bf16_f32 v104, v90, v91
	v_cvt_pk_bf16_f32 v105, v92, v93
	ds_write2_b64 v234, v[102:103], v[104:105] offset1:4
	v_add_u32_e32 v102, 0x140, v192
	v_ashrrev_i32_e32 v103, 31, v102
	v_lshlrev_b64 v[102:103], 12, v[102:103]
	v_lshl_add_u64 v[102:103], v[190:191], 0, v[102:103]
	v_add_co_u32_e32 v104, vcc, s30, v102
	global_store_dword v[102:103], v98, off
	s_nop 0
	v_addc_co_u32_e32 v105, vcc, 0, v103, vcc
	v_add_co_u32_e32 v98, vcc, s31, v102
	global_store_dword v[104:105], v99, off offset:-4096
	global_store_dword v[104:105], v100, off
	v_addc_co_u32_e32 v99, vcc, 0, v103, vcc
	global_store_dword v[98:99], v101, off
	s_waitcnt lgkmcnt(0)
	s_barrier
	v_add_u32_e32 v192, 0x180, v192
	s_cbranch_scc1 .LBB0_888
	ds_read_b128 v[98:101], v237
	ds_read_b128 v[102:105], v237 offset:64
	s_add_u32 s8, s12, 0x3e000
	s_addc_u32 s9, s13, 0
	v_lshl_add_u64 v[106:107], s[8:9], 0, v[180:181]
	s_waitcnt lgkmcnt(1)
	v_mfma_f32_16x16x32_bf16 v[18:21], v[18:21], v[98:101], 0
	v_or_b32_e32 v108, 0x400, v184
	v_add3_u32 v1, v1, s24, v179
	s_movk_i32 s13, 0x2000
	v_mfma_f32_16x16x32_bf16 v[38:41], v[38:41], v[98:101], 0
	v_lshl_add_u64 v[98:99], s[8:9], 0, v[182:183]
	s_add_u32 s8, s10, 0x7c000
	s_addc_u32 s9, s11, 0
	s_waitcnt lgkmcnt(0)
	v_mfma_f32_16x16x32_bf16 v[6:9], v[6:9], v[102:105], v[18:21]
	v_lshl_add_u64 v[100:101], s[8:9], 0, v[184:185]
	v_lshl_add_u64 v[110:111], s[8:9], 0, v[188:189]
	s_lshl_b32 s10, s23, 2
	ds_read_b128 v[18:21], v237 offset:128
	v_mfma_f32_16x16x32_bf16 v[2:5], v[2:5], v[102:105], v[38:41]
	s_nop 2
	global_load_dwordx4 v[38:41], v[98:99], off
	s_nop 0
	global_load_dwordx4 v[98:101], v[100:101], off
	ds_read_b128 v[102:105], v237 offset:192
	s_movk_i32 s16, 0x3000
	s_waitcnt lgkmcnt(1)
	v_mfma_f32_16x16x32_bf16 v[6:9], v[26:29], v[18:21], v[6:9]
	global_load_dwordx4 v[26:29], v[106:107], off
	s_nop 0
	global_load_dwordx4 v[106:109], v108, s[8:9]
	v_readlane_b32 s12, v177, 31
	s_lshl_b64 s[4:5], s[4:5], 7
	v_mfma_f32_16x16x32_bf16 v[2:5], v[14:17], v[18:21], v[2:5]
	v_lshl_add_u64 v[18:19], s[8:9], 0, v[186:187]
	global_load_dwordx4 v[14:17], v[110:111], off
	s_nop 0
	global_load_dwordx4 v[18:21], v[18:19], off
	v_readlane_b32 s8, v177, 30
	s_waitcnt lgkmcnt(0)
	v_mfma_f32_16x16x32_bf16 v[6:9], v[22:25], v[102:105], v[6:9]
	v_ashrrev_i32_e32 v177, 31, v176
	v_pk_mul_f32 v[24:25], v[96:97], s[8:9] op_sel_hi:[1,0]
	v_pk_mul_f32 v[22:23], v[94:95], s[8:9] op_sel_hi:[1,0]
	v_mfma_f32_16x16x32_bf16 v[2:5], v[10:13], v[102:105], v[2:5]
	s_nop 3
	v_sub_f32_e32 v9, v240, v9
	v_sub_f32_e32 v8, v239, v8
	v_sub_f32_e32 v7, v238, v7
	v_sub_f32_e32 v6, v193, v6
	v_cvt_pk_bf16_f32 v6, v6, v7
	v_cvt_pk_bf16_f32 v7, v8, v9
	ds_write_b64 v236, v[6:7] offset:4352
	s_waitcnt lgkmcnt(0)
	s_barrier
; DEV void gdn_scan_item(const Params& p, int item, unsigned char* lds) {
;     ...
;     LOAD_E(E0, 0); LOAD_L(L0, 0); LOAD_E(E1, 1);
;     __syncthreads();
;     for (int ch = 0; ch < 30; ch += 6) {
;         SCAN_STEP(E0, E2, L0, L1, ch);     SCAN_STEP(E1, E0, L1, L0, ch + 1); SCAN_STEP(E2, E1, L0, L1, ch + 2);
;         SCAN_STEP(E0, E2, L1, L0, ch + 3); SCAN_STEP(E1, E0, L0, L1, ch + 4); SCAN_STEP(E2, E1, L1, L0, ch + 5);
;     }
;     SCAN_STEP(E0, E2, L0, L1, 30); SCAN_STEP(E1, E0, L1, L0, 31);
;     ...
;     {
;         float* dp = p.out + O_DP + ((size_t)bh * 128 + w * 32 + fq * 4) * 128 + s * 16 + fr;
; #pragma unroll
;         for (int e = 0; e < 4; ++e) { dp[e * 128] = S0[e]; dp[(16 + e) * 128] = S1[e]; }
;     }
;     __syncthreads();
	ds_read_b128 v[6:9], v235 offset:4352
	ds_read_b128 v[10:13], v235 offset:4416
	s_waitcnt vmcnt(13) lgkmcnt(1)
	v_mfma_f32_16x16x32_bf16 v[22:25], v[70:73], v[6:9], v[22:25]
	v_mul_f32_e64 v72, v92, s8
	v_mul_f32_e64 v73, v93, s8
	v_pk_mul_f32 v[70:71], v[90:91], s[8:9] op_sel_hi:[1,0]
	s_mov_b32 s9, 0
	v_mfma_f32_16x16x32_bf16 v[2:5], v[86:89], v[6:9], v[2:5]
	s_lshl_b32 s8, s22, 2
	s_mov_b32 s11, s9
	s_waitcnt vmcnt(11)
	v_mfma_f32_16x16x32_bf16 v[6:9], v[66:69], v[6:9], v[70:73]
	s_waitcnt lgkmcnt(0)
	v_mfma_f32_16x16x32_bf16 v[22:25], v[82:85], v[10:13], v[22:25]
	s_waitcnt vmcnt(10)
	v_mfma_f32_16x16x32_bf16 v[6:9], v[78:81], v[10:13], v[6:9]
	v_mfma_f32_16x16x32_bf16 v[2:5], v[74:77], v[10:13], v[2:5]
	v_add_u32_e32 v10, 0x780, v1
	v_ashrrev_i32_e32 v11, 31, v10
	v_lshlrev_b64 v[10:11], 12, v[10:11]
	v_lshl_add_u64 v[10:11], s[6:7], 0, v[10:11]
	s_nop 0
	v_cvt_pk_bf16_f32 v66, v22, v23
	v_cvt_pk_bf16_f32 v67, v24, v25
	v_cvt_pk_bf16_f32 v68, v6, v7
	v_cvt_pk_bf16_f32 v69, v8, v9
	v_lshl_add_u64 v[10:11], v[10:11], 0, s[8:9]
	ds_write2_b64 v234, v[66:67], v[68:69] offset1:4
	v_lshl_add_u64 v[10:11], v[10:11], 0, s[10:11]
	v_lshlrev_b32_e32 v66, 2, v178
	v_mov_b32_e32 v67, 0
	v_lshl_add_u64 v[10:11], v[10:11], 0, v[66:67]
	v_add_co_u32_e32 v12, vcc, s13, v10
	global_store_dword v[10:11], v2, off
	s_nop 0
	v_addc_co_u32_e32 v13, vcc, 0, v11, vcc
	v_add_co_u32_e32 v2, vcc, s16, v10
	global_store_dword v[12:13], v3, off offset:-4096
	global_store_dword v[12:13], v4, off
	v_addc_co_u32_e32 v3, vcc, 0, v11, vcc
	global_store_dword v[2:3], v5, off
	s_waitcnt lgkmcnt(0)
	s_barrier
	ds_read_b128 v[2:5], v237
	ds_read_b128 v[10:13], v237 offset:64
	s_waitcnt lgkmcnt(1)
	v_mfma_f32_16x16x32_bf16 v[30:33], v[30:33], v[2:5], 0
	v_mul_f32_e64 v24, v24, s12
	v_mul_f32_e64 v25, v25, s12
	v_pk_mul_f32 v[22:23], v[22:23], s[12:13] op_sel_hi:[1,0]
	v_pk_mul_f32 v[8:9], v[8:9], s[12:13] op_sel_hi:[1,0]
	v_mfma_f32_16x16x32_bf16 v[2:5], v[34:37], v[2:5], 0
	v_mul_f32_e64 v6, v6, s12
	v_mul_f32_e64 v7, v7, s12
	s_waitcnt lgkmcnt(0)
	v_mfma_f32_16x16x32_bf16 v[30:33], v[46:49], v[10:13], v[30:33]
	v_mfma_f32_16x16x32_bf16 v[2:5], v[50:53], v[10:13], v[2:5]
	ds_read_b128 v[10:13], v237 offset:128
	ds_read_b128 v[34:37], v237 offset:192
	s_waitcnt lgkmcnt(1)
	v_mfma_f32_16x16x32_bf16 v[30:33], v[42:45], v[10:13], v[30:33]
	v_mfma_f32_16x16x32_bf16 v[2:5], v[54:57], v[10:13], v[2:5]
	s_waitcnt lgkmcnt(0)
	v_mfma_f32_16x16x32_bf16 v[10:13], v[58:61], v[34:37], v[30:33]
	v_mfma_f32_16x16x32_bf16 v[2:5], v[62:65], v[34:37], v[2:5]
	s_nop 6
	v_sub_f32_e32 v13, v156, v13
	v_sub_f32_e32 v12, v155, v12
	v_sub_f32_e32 v11, v154, v11
	v_sub_f32_e32 v10, v157, v10
	v_cvt_pk_bf16_f32 v10, v10, v11
	v_cvt_pk_bf16_f32 v11, v12, v13
	ds_write_b64 v236, v[10:11] offset:4352
	s_waitcnt lgkmcnt(0)
	s_barrier
	ds_read_b128 v[10:13], v235 offset:4352
	ds_read_b128 v[30:33], v235 offset:4416
	s_waitcnt vmcnt(8) lgkmcnt(1)
	v_mfma_f32_16x16x32_bf16 v[22:25], v[98:101], v[10:13], v[22:25]
	s_waitcnt vmcnt(6)
	v_mfma_f32_16x16x32_bf16 v[6:9], v[106:109], v[10:13], v[6:9]
	s_waitcnt vmcnt(5) lgkmcnt(0)
	v_mfma_f32_16x16x32_bf16 v[14:17], v[14:17], v[30:33], v[22:25]
	s_waitcnt vmcnt(4)
	v_mfma_f32_16x16x32_bf16 v[6:9], v[18:21], v[30:33], v[6:9]
	v_mfma_f32_16x16x32_bf16 v[2:5], v[26:29], v[10:13], v[2:5]
	s_nop 4
	v_cvt_pk_bf16_f32 v10, v14, v15
	v_cvt_pk_bf16_f32 v11, v16, v17
	v_cvt_pk_bf16_f32 v12, v6, v7
	v_cvt_pk_bf16_f32 v13, v8, v9
	ds_write2_b64 v234, v[10:11], v[12:13] offset1:4
	v_add_u32_e32 v10, 0x7c0, v1
	v_ashrrev_i32_e32 v11, 31, v10
	v_lshlrev_b64 v[10:11], 12, v[10:11]
	v_lshl_add_u64 v[10:11], s[6:7], 0, v[10:11]
	v_lshl_add_u64 v[10:11], v[10:11], 0, s[8:9]
	v_mfma_f32_16x16x32_bf16 v[2:5], v[38:41], v[30:33], v[2:5]
	v_lshl_add_u64 v[10:11], v[10:11], 0, s[10:11]
	v_lshl_add_u64 v[10:11], v[10:11], 0, v[66:67]
	v_add_co_u32_e32 v12, vcc, s13, v10
	s_nop 1
	v_addc_co_u32_e32 v13, vcc, 0, v11, vcc
	s_nop 1
	global_store_dword v[10:11], v2, off
	v_add_co_u32_e32 v2, vcc, s16, v10
	global_store_dword v[12:13], v3, off offset:-4096
	global_store_dword v[12:13], v4, off
	v_addc_co_u32_e32 v3, vcc, 0, v11, vcc
	global_store_dword v[2:3], v5, off
	s_waitcnt lgkmcnt(0)
	s_barrier
	s_load_dwordx2 s[6:7], s[0:1], 0xc0
	v_lshl_add_u64 v[2:3], s[4:5], 0, v[176:177]
	v_or_b32_e32 v2, v2, v179
	v_lshlrev_b64 v[2:3], 9, v[2:3]
	s_mov_b64 s[4:5], 0x5400000
	s_waitcnt lgkmcnt(0)
	v_lshl_add_u64 v[2:3], s[6:7], 0, v[2:3]
	v_lshl_add_u64 v[2:3], v[2:3], 0, s[10:11]
	v_lshl_add_u64 v[2:3], v[2:3], 0, v[66:67]
	v_lshl_add_u64 v[4:5], v[2:3], 0, s[4:5]
	s_mov_b32 s4, 0x5400000
	v_add_co_u32_e32 v10, vcc, s4, v2
	s_nop 1
	v_addc_co_u32_e32 v11, vcc, 0, v3, vcc
	v_add_co_u32_e32 v2, vcc, 0x5402000, v2
	global_store_dword v[10:11], v14, off
	s_nop 0
	v_addc_co_u32_e32 v3, vcc, 0, v3, vcc
	global_store_dword v[2:3], v6, off
	global_store_dword v[4:5], v15, off offset:512
	global_store_dword v[2:3], v7, off offset:512
	global_store_dword v[4:5], v16, off offset:1024
	global_store_dword v[2:3], v8, off offset:1024
	global_store_dword v[4:5], v17, off offset:1536
	global_store_dword v[2:3], v9, off offset:1536
	v_mov_b32_e32 v252, v254
	s_cmp_lg_u32 s71, 0
	s_cbranch_scc1 .Lscan_stag1
	s_barrier
